# in/up epilogue row scale: v_rsq_f32 (f32) instead of hipcc's 28-instruction IEEE sqrt+divide sequence for 1/sqrtf(x)
# speedup vs baseline: 1.0351x; 1.0037x over previous
.LBB0_216:
	v_lshl_add_u32 v144, s40, 8, v156
	v_ashrrev_i32_e32 v145, 31, v144
	v_lshl_add_u64 v[146:147], v[144:145], 2, s[44:45]
	global_load_dword v141, v[146:147], off
	global_load_dword v164, v[146:147], off offset:64
	global_load_dword v165, v[146:147], off offset:128
	global_load_dword v166, v[146:147], off offset:192
	global_load_dword v167, v[146:147], off offset:512
	global_load_dword v168, v[146:147], off offset:576
	global_load_dword v169, v[146:147], off offset:640
	global_load_dword v170, v[146:147], off offset:704
	v_lshl_or_b32 v142, s30, 8, v158
	v_ashrrev_i32_e32 v143, 31, v142
	s_cmp_lg_u64 s[22:23], 0
	v_add_u32_e32 v140, s31, v142
	s_cselect_b64 s[42:43], -1, 0
	s_cmp_eq_u64 s[22:23], 0
	s_waitcnt vmcnt(0)
	v_fmamk_f32 v141, v141, 0x3a800000, v235
	v_add_u32_e32 v152, s9, v144
	v_mov_b64_e32 v[150:151], s[20:21]
	v_ashrrev_i32_e32 v153, 31, v152
	v_rsq_f32_e32 v148, v141
	s_nop 0
	v_mad_i64_i32 v[150:151], s[10:11], v144, s84, v[150:151]
	v_lshlrev_b64 v[152:153], 11, v[152:153]
	v_lshl_add_u64 v[150:151], v[142:143], 1, v[150:151]
	v_lshl_add_u64 v[152:153], s[22:23], 0, v[152:153]
	v_pk_mul_f32 v[126:127], v[126:127], v[148:149] op_sel_hi:[1,0]
	v_pk_mul_f32 v[124:125], v[124:125], v[148:149] op_sel_hi:[1,0]
	v_pk_mul_f32 v[122:123], v[122:123], v[148:149] op_sel_hi:[1,0]
	v_pk_mul_f32 v[120:121], v[120:121], v[148:149] op_sel_hi:[1,0]
	v_ashrrev_i32_e32 v141, 31, v140
	v_cvt_pk_bf16_f32 v160, v124, v125
	v_cvt_pk_bf16_f32 v161, v126, v127
	v_cvt_pk_bf16_f32 v162, v120, v121
	v_cvt_pk_bf16_f32 v163, v122, v123
	global_store_dwordx4 v[150:151], v[160:163], off
	s_cbranch_scc1 .LBB0_218
	s_nop 0
	v_lshl_add_u64 v[160:161], v[140:141], 2, v[152:153]
	global_store_dwordx4 v[160:161], v[124:127], off nt
	global_store_dwordx4 v[160:161], v[120:123], off offset:16 nt

.LBB0_222:
	s_nop 1
	v_mov_b32_e32 v113, v164
	s_nop 0
	v_or_b32_e32 v112, 16, v144
	v_fmamk_f32 v113, v113, 0x3a800000, v235
	v_add_u32_e32 v118, s9, v112
	v_mov_b64_e32 v[116:117], s[20:21]
	v_ashrrev_i32_e32 v119, 31, v118
	v_rsq_f32_e32 v114, v113
	s_nop 0
	v_mad_i64_i32 v[116:117], s[10:11], v112, s84, v[116:117]
	v_lshlrev_b64 v[118:119], 11, v[118:119]
	v_lshl_add_u64 v[116:117], v[142:143], 1, v[116:117]
	v_lshl_add_u64 v[118:119], s[22:23], 0, v[118:119]
	v_pk_mul_f32 v[110:111], v[110:111], v[114:115] op_sel_hi:[1,0]
	v_pk_mul_f32 v[108:109], v[108:109], v[114:115] op_sel_hi:[1,0]
	v_pk_mul_f32 v[106:107], v[106:107], v[114:115] op_sel_hi:[1,0]
	v_pk_mul_f32 v[104:105], v[104:105], v[114:115] op_sel_hi:[1,0]
	s_and_b64 vcc, exec, s[40:41]
	v_cvt_pk_bf16_f32 v120, v108, v109
	v_cvt_pk_bf16_f32 v121, v110, v111
	v_cvt_pk_bf16_f32 v122, v104, v105
	v_cvt_pk_bf16_f32 v123, v106, v107
	global_store_dwordx4 v[116:117], v[120:123], off
	s_cbranch_vccnz .LBB0_224
	s_nop 0
	v_lshl_add_u64 v[120:121], v[140:141], 2, v[118:119]
	global_store_dwordx4 v[120:121], v[108:111], off nt
	global_store_dwordx4 v[120:121], v[104:107], off offset:16 nt

.LBB0_228:
	s_nop 1
	v_mov_b32_e32 v97, v165
	s_nop 0
	v_or_b32_e32 v96, 32, v144
	v_fmamk_f32 v97, v97, 0x3a800000, v235
	v_add_u32_e32 v102, s9, v96
	v_mov_b64_e32 v[100:101], s[20:21]
	v_ashrrev_i32_e32 v103, 31, v102
	v_rsq_f32_e32 v98, v97
	s_nop 0
	v_mad_i64_i32 v[100:101], s[10:11], v96, s84, v[100:101]
	v_lshlrev_b64 v[102:103], 11, v[102:103]
	v_lshl_add_u64 v[100:101], v[142:143], 1, v[100:101]
	v_lshl_add_u64 v[102:103], s[22:23], 0, v[102:103]
	v_pk_mul_f32 v[94:95], v[94:95], v[98:99] op_sel_hi:[1,0]
	v_pk_mul_f32 v[92:93], v[92:93], v[98:99] op_sel_hi:[1,0]
	v_pk_mul_f32 v[90:91], v[90:91], v[98:99] op_sel_hi:[1,0]
	v_pk_mul_f32 v[88:89], v[88:89], v[98:99] op_sel_hi:[1,0]
	s_and_b64 vcc, exec, s[40:41]
	v_cvt_pk_bf16_f32 v104, v92, v93
	v_cvt_pk_bf16_f32 v105, v94, v95
	v_cvt_pk_bf16_f32 v106, v88, v89
	v_cvt_pk_bf16_f32 v107, v90, v91
	global_store_dwordx4 v[100:101], v[104:107], off
	s_cbranch_vccnz .LBB0_230
	s_nop 0
	v_lshl_add_u64 v[104:105], v[140:141], 2, v[102:103]
	global_store_dwordx4 v[104:105], v[92:95], off nt
	global_store_dwordx4 v[104:105], v[88:91], off offset:16 nt

.LBB0_234:
	s_nop 1
	v_mov_b32_e32 v81, v166
	s_nop 0
	v_or_b32_e32 v80, 48, v144
	v_fmamk_f32 v81, v81, 0x3a800000, v235
	v_add_u32_e32 v86, s9, v80
	v_mov_b64_e32 v[84:85], s[20:21]
	v_ashrrev_i32_e32 v87, 31, v86
	v_rsq_f32_e32 v82, v81
	s_nop 0
	v_mad_i64_i32 v[84:85], s[10:11], v80, s84, v[84:85]
	v_lshlrev_b64 v[86:87], 11, v[86:87]
	v_lshl_add_u64 v[84:85], v[142:143], 1, v[84:85]
	v_lshl_add_u64 v[86:87], s[22:23], 0, v[86:87]
	v_pk_mul_f32 v[78:79], v[78:79], v[82:83] op_sel_hi:[1,0]
	v_pk_mul_f32 v[76:77], v[76:77], v[82:83] op_sel_hi:[1,0]
	v_pk_mul_f32 v[74:75], v[74:75], v[82:83] op_sel_hi:[1,0]
	v_pk_mul_f32 v[72:73], v[72:73], v[82:83] op_sel_hi:[1,0]
	s_and_b64 vcc, exec, s[40:41]
	v_cvt_pk_bf16_f32 v88, v76, v77
	v_cvt_pk_bf16_f32 v89, v78, v79
	v_cvt_pk_bf16_f32 v90, v72, v73
	v_cvt_pk_bf16_f32 v91, v74, v75
	global_store_dwordx4 v[84:85], v[88:91], off
	s_cbranch_vccnz .LBB0_236
	s_nop 0
	v_lshl_add_u64 v[88:89], v[140:141], 2, v[86:87]
	global_store_dwordx4 v[88:89], v[76:79], off nt
	global_store_dwordx4 v[88:89], v[72:75], off offset:16 nt

.LBB0_240:
	s_nop 1
	v_mov_b32_e32 v65, v167
	s_nop 0
	v_add_u32_e32 v64, 0x80, v144
	v_fmamk_f32 v65, v65, 0x3a800000, v235
	v_add_u32_e32 v70, s9, v64
	v_mov_b64_e32 v[68:69], s[20:21]
	v_ashrrev_i32_e32 v71, 31, v70
	v_rsq_f32_e32 v66, v65
	s_nop 0
	v_mad_i64_i32 v[68:69], s[10:11], v64, s84, v[68:69]
	v_lshlrev_b64 v[70:71], 11, v[70:71]
	v_lshl_add_u64 v[68:69], v[142:143], 1, v[68:69]
	v_lshl_add_u64 v[70:71], s[22:23], 0, v[70:71]
	v_pk_mul_f32 v[62:63], v[62:63], v[66:67] op_sel_hi:[1,0]
	v_pk_mul_f32 v[60:61], v[60:61], v[66:67] op_sel_hi:[1,0]
	v_pk_mul_f32 v[58:59], v[58:59], v[66:67] op_sel_hi:[1,0]
	v_pk_mul_f32 v[56:57], v[56:57], v[66:67] op_sel_hi:[1,0]
	s_and_b64 vcc, exec, s[40:41]
	v_cvt_pk_bf16_f32 v72, v60, v61
	v_cvt_pk_bf16_f32 v73, v62, v63
	v_cvt_pk_bf16_f32 v74, v56, v57
	v_cvt_pk_bf16_f32 v75, v58, v59
	global_store_dwordx4 v[68:69], v[72:75], off
	s_cbranch_vccnz .LBB0_242
	s_nop 0
	v_lshl_add_u64 v[72:73], v[140:141], 2, v[70:71]
	global_store_dwordx4 v[72:73], v[60:63], off nt
	global_store_dwordx4 v[72:73], v[56:59], off offset:16 nt

.LBB0_246:
	s_nop 1
	v_mov_b32_e32 v49, v168
	s_nop 0
	v_add_u32_e32 v48, 0x90, v144
	v_fmamk_f32 v49, v49, 0x3a800000, v235
	v_add_u32_e32 v54, s9, v48
	v_mov_b64_e32 v[52:53], s[20:21]
	v_ashrrev_i32_e32 v55, 31, v54
	v_rsq_f32_e32 v50, v49
	s_nop 0
	v_mad_i64_i32 v[52:53], s[10:11], v48, s84, v[52:53]
	v_lshlrev_b64 v[54:55], 11, v[54:55]
	v_lshl_add_u64 v[52:53], v[142:143], 1, v[52:53]
	v_lshl_add_u64 v[54:55], s[22:23], 0, v[54:55]
	v_pk_mul_f32 v[46:47], v[46:47], v[50:51] op_sel_hi:[1,0]
	v_pk_mul_f32 v[44:45], v[44:45], v[50:51] op_sel_hi:[1,0]
	v_pk_mul_f32 v[42:43], v[42:43], v[50:51] op_sel_hi:[1,0]
	v_pk_mul_f32 v[40:41], v[40:41], v[50:51] op_sel_hi:[1,0]
	s_and_b64 vcc, exec, s[40:41]
	v_cvt_pk_bf16_f32 v56, v44, v45
	v_cvt_pk_bf16_f32 v57, v46, v47
	v_cvt_pk_bf16_f32 v58, v40, v41
	v_cvt_pk_bf16_f32 v59, v42, v43
	global_store_dwordx4 v[52:53], v[56:59], off
	s_cbranch_vccnz .LBB0_248
	s_nop 0
	v_lshl_add_u64 v[56:57], v[140:141], 2, v[54:55]
	global_store_dwordx4 v[56:57], v[44:47], off nt
	global_store_dwordx4 v[56:57], v[40:43], off offset:16 nt

.LBB0_252:
	s_nop 1
	v_mov_b32_e32 v33, v169
	s_nop 0
	v_add_u32_e32 v32, 0xa0, v144
	v_fmamk_f32 v33, v33, 0x3a800000, v235
	v_add_u32_e32 v38, s9, v32
	v_mov_b64_e32 v[36:37], s[20:21]
	v_ashrrev_i32_e32 v39, 31, v38
	v_rsq_f32_e32 v34, v33
	s_nop 0
	v_mad_i64_i32 v[36:37], s[10:11], v32, s84, v[36:37]
	v_lshlrev_b64 v[38:39], 11, v[38:39]
	v_lshl_add_u64 v[36:37], v[142:143], 1, v[36:37]
	v_lshl_add_u64 v[38:39], s[22:23], 0, v[38:39]
	v_pk_mul_f32 v[30:31], v[30:31], v[34:35] op_sel_hi:[1,0]
	v_pk_mul_f32 v[28:29], v[28:29], v[34:35] op_sel_hi:[1,0]
	v_pk_mul_f32 v[26:27], v[26:27], v[34:35] op_sel_hi:[1,0]
	v_pk_mul_f32 v[24:25], v[24:25], v[34:35] op_sel_hi:[1,0]
	s_and_b64 vcc, exec, s[40:41]
	v_cvt_pk_bf16_f32 v40, v28, v29
	v_cvt_pk_bf16_f32 v41, v30, v31
	v_cvt_pk_bf16_f32 v42, v24, v25
	v_cvt_pk_bf16_f32 v43, v26, v27
	global_store_dwordx4 v[36:37], v[40:43], off
	s_cbranch_vccnz .LBB0_254
	s_nop 0
	v_lshl_add_u64 v[40:41], v[140:141], 2, v[38:39]
	global_store_dwordx4 v[40:41], v[28:31], off nt
	global_store_dwordx4 v[40:41], v[24:27], off offset:16 nt

.LBB0_258:
	s_nop 1
	v_mov_b32_e32 v17, v170
	s_nop 0
	v_add_u32_e32 v16, 0xb0, v144
	v_fmamk_f32 v17, v17, 0x3a800000, v235
	v_add_u32_e32 v22, s9, v16
	v_mov_b64_e32 v[20:21], s[20:21]
	v_ashrrev_i32_e32 v23, 31, v22
	v_rsq_f32_e32 v18, v17
	s_nop 0
	v_mad_i64_i32 v[20:21], s[10:11], v16, s84, v[20:21]
	v_lshlrev_b64 v[22:23], 11, v[22:23]
	v_lshl_add_u64 v[20:21], v[142:143], 1, v[20:21]
	v_lshl_add_u64 v[22:23], s[22:23], 0, v[22:23]
	v_pk_mul_f32 v[14:15], v[14:15], v[18:19] op_sel_hi:[1,0]
	v_pk_mul_f32 v[12:13], v[12:13], v[18:19] op_sel_hi:[1,0]
	v_pk_mul_f32 v[10:11], v[10:11], v[18:19] op_sel_hi:[1,0]
	v_pk_mul_f32 v[8:9], v[8:9], v[18:19] op_sel_hi:[1,0]
	s_and_b64 vcc, exec, s[40:41]
	v_cvt_pk_bf16_f32 v24, v12, v13
	v_cvt_pk_bf16_f32 v25, v14, v15
	v_cvt_pk_bf16_f32 v26, v8, v9
	v_cvt_pk_bf16_f32 v27, v10, v11
	global_store_dwordx4 v[20:21], v[24:27], off
	s_cbranch_vccnz .LBB0_260
	s_nop 0
	v_lshl_add_u64 v[24:25], v[140:141], 2, v[22:23]
	global_store_dwordx4 v[24:25], v[12:15], off nt
	global_store_dwordx4 v[24:25], v[8:11], off offset:16 nt

.LBB0_1147:
	v_lshl_add_u32 v144, s22, 8, v149
	v_ashrrev_i32_e32 v145, 31, v144
	v_lshl_add_u64 v[138:139], v[144:145], 2, s[34:35]
	global_load_dword v142, v[138:139], off
	global_load_dword v164, v[138:139], off offset:64
	global_load_dword v165, v[138:139], off offset:128
	global_load_dword v166, v[138:139], off offset:192
	global_load_dword v167, v[138:139], off offset:512
	global_load_dword v168, v[138:139], off offset:576
	global_load_dword v169, v[138:139], off offset:640
	global_load_dword v170, v[138:139], off offset:704
	v_lshl_or_b32 v140, s4, 8, v151
	v_ashrrev_i32_e32 v141, 31, v140
	s_mov_b64 s[22:23], -1
	s_waitcnt vmcnt(0)
	v_fmamk_f32 v142, v142, 0x3a800000, v235
	v_rsq_f32_e32 v146, v142
	s_nop 0
	v_pk_mul_f32 v[120:121], v[120:121], v[146:147] op_sel_hi:[1,0]
	v_pk_mul_f32 v[124:125], v[124:125], v[146:147] op_sel_hi:[1,0]
	v_pk_mul_f32 v[122:123], v[122:123], v[146:147] op_sel_hi:[1,0]
	v_max_f32_e32 v120, 0, v120
	v_lshlrev_b64 v[142:143], 13, v[144:145]
	v_pk_mul_f32 v[126:127], v[126:127], v[146:147] op_sel_hi:[1,0]
	v_mul_f32_e32 v145, v120, v120
	v_max_f32_e32 v120, 0, v125
	v_max_f32_e32 v121, 0, v121
	v_max_f32_e32 v122, 0, v122
	v_lshl_add_u64 v[154:155], s[36:37], 0, v[142:143]
	v_lshlrev_b64 v[142:143], 1, v[140:141]
	v_max_f32_e32 v124, 0, v124
	v_mul_f32_e32 v120, v120, v120
	v_mul_f32_e32 v125, v121, v121
	v_max_f32_e32 v121, 0, v126
	v_mul_f32_e32 v126, v122, v122
	v_max_f32_e32 v122, 0, v127
	v_max_f32_e32 v123, 0, v123
	v_pk_mul_f32 v[114:115], v[114:115], v[146:147] op_sel_hi:[1,0]
	v_pk_mul_f32 v[112:113], v[112:113], v[146:147] op_sel_hi:[1,0]
	v_lshl_add_u64 v[140:141], v[154:155], 0, v[142:143]
	v_mul_f32_e32 v124, v124, v124
	v_mul_f32_e32 v121, v121, v121
	v_mul_f32_e32 v122, v122, v122
	v_mul_f32_e32 v123, v123, v123
	v_cvt_pk_bf16_f32 v120, v124, v120
	v_pk_mul_f32 v[118:119], v[118:119], v[146:147] op_sel_hi:[1,0]
	v_pk_mul_f32 v[116:117], v[116:117], v[146:147] op_sel_hi:[1,0]
	v_max_f32_e32 v112, 0, v112
	v_max_f32_e32 v113, 0, v113
	v_max_f32_e32 v114, 0, v114
	v_cvt_pk_bf16_f32 v121, v121, v122
	v_cvt_pk_bf16_f32 v122, v145, v125
	v_cvt_pk_bf16_f32 v123, v126, v123
	global_store_dwordx4 v[140:141], v[120:123], off
	v_max_f32_e32 v115, 0, v115
	v_max_f32_e32 v116, 0, v116
	v_mul_f32_e32 v120, v112, v112
	v_max_f32_e32 v112, 0, v117
	v_mul_f32_e32 v117, v113, v113
	v_max_f32_e32 v113, 0, v118
	v_mul_f32_e32 v118, v114, v114
	v_max_f32_e32 v114, 0, v119
	v_mul_f32_e32 v112, v112, v112
	v_mul_f32_e32 v113, v113, v113
	v_mul_f32_e32 v114, v114, v114
	v_mul_f32_e32 v115, v115, v115
	v_mul_f32_e32 v116, v116, v116
	v_cvt_pk_bf16_f32 v112, v116, v112
	v_cvt_pk_bf16_f32 v113, v113, v114
	v_cvt_pk_bf16_f32 v114, v120, v117
	v_cvt_pk_bf16_f32 v115, v118, v115
	global_store_dwordx4 v[140:141], v[112:115], off offset:256
	s_nop 1
	v_mov_b32_e32 v112, v164
	s_nop 0
	v_or_b32_e32 v114, 16, v144
	v_ashrrev_i32_e32 v115, 31, v114
	v_lshlrev_b64 v[114:115], 13, v[114:115]
	v_lshl_add_u64 v[114:115], s[36:37], 0, v[114:115]
	v_lshl_add_u64 v[114:115], v[114:115], 0, v[142:143]
	v_fmamk_f32 v112, v112, 0x3a800000, v235
	v_rsq_f32_e32 v112, v112
	s_nop 0
	v_pk_mul_f32 v[104:105], v[104:105], v[112:113] op_sel_hi:[1,0]
	v_pk_mul_f32 v[108:109], v[108:109], v[112:113] op_sel_hi:[1,0]
	v_pk_mul_f32 v[106:107], v[106:107], v[112:113] op_sel_hi:[1,0]
	v_max_f32_e32 v104, 0, v104
	v_pk_mul_f32 v[110:111], v[110:111], v[112:113] op_sel_hi:[1,0]
	v_mul_f32_e32 v113, v104, v104
	v_max_f32_e32 v104, 0, v109
	v_max_f32_e32 v105, 0, v105
	v_max_f32_e32 v106, 0, v106
	v_max_f32_e32 v108, 0, v108
	v_mul_f32_e32 v104, v104, v104
	v_mul_f32_e32 v109, v105, v105
	v_max_f32_e32 v105, 0, v110
	v_mul_f32_e32 v110, v106, v106
	v_max_f32_e32 v106, 0, v111
	v_max_f32_e32 v107, 0, v107
	v_pk_mul_f32 v[98:99], v[98:99], v[112:113] op_sel_hi:[1,0]
	v_pk_mul_f32 v[96:97], v[96:97], v[112:113] op_sel_hi:[1,0]
	v_mul_f32_e32 v108, v108, v108
	v_mul_f32_e32 v105, v105, v105
	v_mul_f32_e32 v106, v106, v106
	v_mul_f32_e32 v107, v107, v107
	v_cvt_pk_bf16_f32 v104, v108, v104
	v_pk_mul_f32 v[102:103], v[102:103], v[112:113] op_sel_hi:[1,0]
	v_pk_mul_f32 v[100:101], v[100:101], v[112:113] op_sel_hi:[1,0]
	v_max_f32_e32 v96, 0, v96
	v_max_f32_e32 v97, 0, v97
	v_max_f32_e32 v98, 0, v98
	v_cvt_pk_bf16_f32 v105, v105, v106
	v_cvt_pk_bf16_f32 v106, v113, v109
	v_cvt_pk_bf16_f32 v107, v110, v107
	global_store_dwordx4 v[114:115], v[104:107], off
	v_max_f32_e32 v99, 0, v99
	v_max_f32_e32 v100, 0, v100
	v_mul_f32_e32 v104, v96, v96
	v_max_f32_e32 v96, 0, v101
	v_mul_f32_e32 v101, v97, v97
	v_max_f32_e32 v97, 0, v102
	v_mul_f32_e32 v102, v98, v98
	v_max_f32_e32 v98, 0, v103
	v_mul_f32_e32 v96, v96, v96
	v_mul_f32_e32 v97, v97, v97
	v_mul_f32_e32 v98, v98, v98
	v_mul_f32_e32 v99, v99, v99
	v_mul_f32_e32 v100, v100, v100
	v_cvt_pk_bf16_f32 v96, v100, v96
	v_cvt_pk_bf16_f32 v97, v97, v98
	v_cvt_pk_bf16_f32 v98, v104, v101
	v_cvt_pk_bf16_f32 v99, v102, v99
	global_store_dwordx4 v[114:115], v[96:99], off offset:256
	s_nop 1
	v_mov_b32_e32 v96, v165
	s_nop 0
	v_or_b32_e32 v98, 32, v144
	v_ashrrev_i32_e32 v99, 31, v98
	v_lshlrev_b64 v[98:99], 13, v[98:99]
	v_lshl_add_u64 v[98:99], s[36:37], 0, v[98:99]
	v_lshl_add_u64 v[98:99], v[98:99], 0, v[142:143]
	v_fmamk_f32 v96, v96, 0x3a800000, v235
	v_rsq_f32_e32 v96, v96
	s_nop 0
	v_pk_mul_f32 v[88:89], v[88:89], v[96:97] op_sel_hi:[1,0]
	v_pk_mul_f32 v[92:93], v[92:93], v[96:97] op_sel_hi:[1,0]
	v_pk_mul_f32 v[90:91], v[90:91], v[96:97] op_sel_hi:[1,0]
	v_max_f32_e32 v88, 0, v88
	v_pk_mul_f32 v[94:95], v[94:95], v[96:97] op_sel_hi:[1,0]
	v_mul_f32_e32 v97, v88, v88
	v_max_f32_e32 v88, 0, v93
	v_max_f32_e32 v89, 0, v89
	v_max_f32_e32 v90, 0, v90
	v_max_f32_e32 v92, 0, v92
	v_mul_f32_e32 v88, v88, v88
	v_mul_f32_e32 v93, v89, v89
	v_max_f32_e32 v89, 0, v94
	v_mul_f32_e32 v94, v90, v90
	v_max_f32_e32 v90, 0, v95
	v_max_f32_e32 v91, 0, v91
	v_pk_mul_f32 v[82:83], v[82:83], v[96:97] op_sel_hi:[1,0]
	v_pk_mul_f32 v[80:81], v[80:81], v[96:97] op_sel_hi:[1,0]
	v_mul_f32_e32 v92, v92, v92
	v_mul_f32_e32 v89, v89, v89
	v_mul_f32_e32 v90, v90, v90
	v_mul_f32_e32 v91, v91, v91
	v_cvt_pk_bf16_f32 v88, v92, v88
	v_pk_mul_f32 v[86:87], v[86:87], v[96:97] op_sel_hi:[1,0]
	v_pk_mul_f32 v[84:85], v[84:85], v[96:97] op_sel_hi:[1,0]
	v_max_f32_e32 v80, 0, v80
	v_max_f32_e32 v81, 0, v81
	v_max_f32_e32 v82, 0, v82
	v_cvt_pk_bf16_f32 v89, v89, v90
	v_cvt_pk_bf16_f32 v90, v97, v93
	v_cvt_pk_bf16_f32 v91, v94, v91
	global_store_dwordx4 v[98:99], v[88:91], off
	v_max_f32_e32 v83, 0, v83
	v_max_f32_e32 v84, 0, v84
	v_mul_f32_e32 v88, v80, v80
	v_max_f32_e32 v80, 0, v85
	v_mul_f32_e32 v85, v81, v81
	v_max_f32_e32 v81, 0, v86
	v_mul_f32_e32 v86, v82, v82
	v_max_f32_e32 v82, 0, v87
	v_mul_f32_e32 v80, v80, v80
	v_mul_f32_e32 v81, v81, v81
	v_mul_f32_e32 v82, v82, v82
	v_mul_f32_e32 v83, v83, v83
	v_mul_f32_e32 v84, v84, v84
	v_cvt_pk_bf16_f32 v80, v84, v80
	v_cvt_pk_bf16_f32 v81, v81, v82
	v_cvt_pk_bf16_f32 v82, v88, v85
	v_cvt_pk_bf16_f32 v83, v86, v83
	global_store_dwordx4 v[98:99], v[80:83], off offset:256
	s_nop 1
	v_mov_b32_e32 v80, v166
	s_nop 0
	v_or_b32_e32 v82, 48, v144
	v_ashrrev_i32_e32 v83, 31, v82
	v_lshlrev_b64 v[82:83], 13, v[82:83]
	v_lshl_add_u64 v[82:83], s[36:37], 0, v[82:83]
	v_lshl_add_u64 v[82:83], v[82:83], 0, v[142:143]
	v_fmamk_f32 v80, v80, 0x3a800000, v235
	v_rsq_f32_e32 v80, v80
	s_nop 0
	v_pk_mul_f32 v[72:73], v[72:73], v[80:81] op_sel_hi:[1,0]
	v_pk_mul_f32 v[76:77], v[76:77], v[80:81] op_sel_hi:[1,0]
	v_pk_mul_f32 v[74:75], v[74:75], v[80:81] op_sel_hi:[1,0]
	v_max_f32_e32 v72, 0, v72
	v_pk_mul_f32 v[78:79], v[78:79], v[80:81] op_sel_hi:[1,0]
	v_mul_f32_e32 v81, v72, v72
	v_max_f32_e32 v72, 0, v77
	v_max_f32_e32 v73, 0, v73
	v_max_f32_e32 v74, 0, v74
	v_max_f32_e32 v76, 0, v76
	v_mul_f32_e32 v72, v72, v72
	v_mul_f32_e32 v77, v73, v73
	v_max_f32_e32 v73, 0, v78
	v_mul_f32_e32 v78, v74, v74
	v_max_f32_e32 v74, 0, v79
	v_max_f32_e32 v75, 0, v75
	v_pk_mul_f32 v[66:67], v[66:67], v[80:81] op_sel_hi:[1,0]
	v_pk_mul_f32 v[64:65], v[64:65], v[80:81] op_sel_hi:[1,0]
	v_mul_f32_e32 v76, v76, v76
	v_mul_f32_e32 v73, v73, v73
	v_mul_f32_e32 v74, v74, v74
	v_mul_f32_e32 v75, v75, v75
	v_cvt_pk_bf16_f32 v72, v76, v72
	v_pk_mul_f32 v[70:71], v[70:71], v[80:81] op_sel_hi:[1,0]
	v_pk_mul_f32 v[68:69], v[68:69], v[80:81] op_sel_hi:[1,0]
	v_max_f32_e32 v64, 0, v64
	v_max_f32_e32 v65, 0, v65
	v_max_f32_e32 v66, 0, v66
	v_cvt_pk_bf16_f32 v73, v73, v74
	v_cvt_pk_bf16_f32 v74, v81, v77
	v_cvt_pk_bf16_f32 v75, v78, v75
	global_store_dwordx4 v[82:83], v[72:75], off
	v_max_f32_e32 v67, 0, v67
	v_max_f32_e32 v68, 0, v68
	v_mul_f32_e32 v72, v64, v64
	v_max_f32_e32 v64, 0, v69
	v_mul_f32_e32 v69, v65, v65
	v_max_f32_e32 v65, 0, v70
	v_mul_f32_e32 v70, v66, v66
	v_max_f32_e32 v66, 0, v71
	v_mul_f32_e32 v64, v64, v64
	v_mul_f32_e32 v65, v65, v65
	v_mul_f32_e32 v66, v66, v66
	v_mul_f32_e32 v67, v67, v67
	v_mul_f32_e32 v68, v68, v68
	v_cvt_pk_bf16_f32 v64, v68, v64
	v_cvt_pk_bf16_f32 v65, v65, v66
	v_cvt_pk_bf16_f32 v66, v72, v69
	v_cvt_pk_bf16_f32 v67, v70, v67
	global_store_dwordx4 v[82:83], v[64:67], off offset:256
	s_nop 1
	v_mov_b32_e32 v64, v167
	v_fmamk_f32 v64, v64, 0x3a800000, v235
	s_mov_b64 s[4:5], 0x100000
	v_rsq_f32_e32 v66, v64
	s_nop 0
	v_pk_mul_f32 v[56:57], v[56:57], v[66:67] op_sel_hi:[1,0]
	v_pk_mul_f32 v[60:61], v[60:61], v[66:67] op_sel_hi:[1,0]
	v_pk_mul_f32 v[58:59], v[58:59], v[66:67] op_sel_hi:[1,0]
	v_max_f32_e32 v56, 0, v56
	v_pk_mul_f32 v[62:63], v[62:63], v[66:67] op_sel_hi:[1,0]
	v_max_f32_e32 v60, 0, v60
	v_mul_f32_e32 v67, v56, v56
	v_max_f32_e32 v56, 0, v61
	v_max_f32_e32 v57, 0, v57
	v_max_f32_e32 v58, 0, v58
	v_lshl_add_u64 v[64:65], v[140:141], 0, s[4:5]
	v_mul_f32_e32 v60, v60, v60
	v_mul_f32_e32 v56, v56, v56
	v_mul_f32_e32 v61, v57, v57
	v_max_f32_e32 v57, 0, v62
	v_mul_f32_e32 v62, v58, v58
	v_max_f32_e32 v58, 0, v63
	s_mov_b32 s4, 0x100000
	v_mul_f32_e32 v57, v57, v57
	v_max_f32_e32 v59, 0, v59
	v_mul_f32_e32 v58, v58, v58
	v_cvt_pk_bf16_f32 v56, v60, v56
	v_add_co_u32_e32 v60, vcc, s4, v140
	v_pk_mul_f32 v[50:51], v[50:51], v[66:67] op_sel_hi:[1,0]
	v_pk_mul_f32 v[48:49], v[48:49], v[66:67] op_sel_hi:[1,0]
	v_mul_f32_e32 v59, v59, v59
	v_cvt_pk_bf16_f32 v57, v57, v58
	v_cvt_pk_bf16_f32 v58, v67, v61
	v_addc_co_u32_e32 v61, vcc, 0, v141, vcc
	v_pk_mul_f32 v[54:55], v[54:55], v[66:67] op_sel_hi:[1,0]
	v_pk_mul_f32 v[52:53], v[52:53], v[66:67] op_sel_hi:[1,0]
	v_max_f32_e32 v48, 0, v48
	v_max_f32_e32 v49, 0, v49
	v_max_f32_e32 v50, 0, v50
	v_cvt_pk_bf16_f32 v59, v62, v59
	global_store_dwordx4 v[60:61], v[56:59], off
	v_max_f32_e32 v51, 0, v51
	v_max_f32_e32 v52, 0, v52
	v_mul_f32_e32 v56, v48, v48
	v_max_f32_e32 v48, 0, v53
	v_mul_f32_e32 v53, v49, v49
	v_max_f32_e32 v49, 0, v54
	v_mul_f32_e32 v54, v50, v50
	v_max_f32_e32 v50, 0, v55
	v_mul_f32_e32 v48, v48, v48
	v_mul_f32_e32 v49, v49, v49
	v_mul_f32_e32 v50, v50, v50
	v_mul_f32_e32 v51, v51, v51
	v_mul_f32_e32 v52, v52, v52
	v_cvt_pk_bf16_f32 v48, v52, v48
	v_cvt_pk_bf16_f32 v49, v49, v50
	v_cvt_pk_bf16_f32 v50, v56, v53
	v_cvt_pk_bf16_f32 v51, v54, v51
	global_store_dwordx4 v[64:65], v[48:51], off offset:256
	s_nop 1
	v_mov_b32_e32 v48, v168
	v_fmamk_f32 v48, v48, 0x3a800000, v235
	s_mov_b64 s[4:5], 0x120000
	v_rsq_f32_e32 v50, v48
	s_nop 0
	v_pk_mul_f32 v[40:41], v[40:41], v[50:51] op_sel_hi:[1,0]
	v_pk_mul_f32 v[44:45], v[44:45], v[50:51] op_sel_hi:[1,0]
	v_pk_mul_f32 v[42:43], v[42:43], v[50:51] op_sel_hi:[1,0]
	v_max_f32_e32 v40, 0, v40
	v_pk_mul_f32 v[46:47], v[46:47], v[50:51] op_sel_hi:[1,0]
	v_max_f32_e32 v44, 0, v44
	v_mul_f32_e32 v51, v40, v40
	v_max_f32_e32 v40, 0, v45
	v_max_f32_e32 v41, 0, v41
	v_max_f32_e32 v42, 0, v42
	v_lshl_add_u64 v[48:49], v[140:141], 0, s[4:5]
	v_mul_f32_e32 v44, v44, v44
	v_mul_f32_e32 v40, v40, v40
	v_mul_f32_e32 v45, v41, v41
	v_max_f32_e32 v41, 0, v46
	v_mul_f32_e32 v46, v42, v42
	v_max_f32_e32 v42, 0, v47
	s_mov_b32 s4, 0x120000
	v_mul_f32_e32 v41, v41, v41
	v_max_f32_e32 v43, 0, v43
	v_mul_f32_e32 v42, v42, v42
	v_cvt_pk_bf16_f32 v40, v44, v40
	v_add_co_u32_e32 v44, vcc, s4, v140
	v_pk_mul_f32 v[34:35], v[34:35], v[50:51] op_sel_hi:[1,0]
	v_pk_mul_f32 v[32:33], v[32:33], v[50:51] op_sel_hi:[1,0]
	v_mul_f32_e32 v43, v43, v43
	v_cvt_pk_bf16_f32 v41, v41, v42
	v_cvt_pk_bf16_f32 v42, v51, v45
	v_addc_co_u32_e32 v45, vcc, 0, v141, vcc
	v_pk_mul_f32 v[38:39], v[38:39], v[50:51] op_sel_hi:[1,0]
	v_pk_mul_f32 v[36:37], v[36:37], v[50:51] op_sel_hi:[1,0]
	v_max_f32_e32 v32, 0, v32
	v_max_f32_e32 v33, 0, v33
	v_max_f32_e32 v34, 0, v34
	v_cvt_pk_bf16_f32 v43, v46, v43
	global_store_dwordx4 v[44:45], v[40:43], off
	v_max_f32_e32 v35, 0, v35
	v_max_f32_e32 v36, 0, v36
	v_mul_f32_e32 v40, v32, v32
	v_max_f32_e32 v32, 0, v37
	v_mul_f32_e32 v37, v33, v33
	v_max_f32_e32 v33, 0, v38
	v_mul_f32_e32 v38, v34, v34
	v_max_f32_e32 v34, 0, v39
	v_mul_f32_e32 v32, v32, v32
	v_mul_f32_e32 v33, v33, v33
	v_mul_f32_e32 v34, v34, v34
	v_mul_f32_e32 v35, v35, v35
	v_mul_f32_e32 v36, v36, v36
	v_cvt_pk_bf16_f32 v32, v36, v32
	v_cvt_pk_bf16_f32 v33, v33, v34
	v_cvt_pk_bf16_f32 v34, v40, v37
	v_cvt_pk_bf16_f32 v35, v38, v35
	global_store_dwordx4 v[48:49], v[32:35], off offset:256
	s_nop 1
	v_mov_b32_e32 v32, v169
	v_fmamk_f32 v32, v32, 0x3a800000, v235
	s_mov_b64 s[4:5], 0x140000
	v_rsq_f32_e32 v34, v32
	s_nop 0
	v_pk_mul_f32 v[24:25], v[24:25], v[34:35] op_sel_hi:[1,0]
	v_pk_mul_f32 v[28:29], v[28:29], v[34:35] op_sel_hi:[1,0]
	v_pk_mul_f32 v[26:27], v[26:27], v[34:35] op_sel_hi:[1,0]
	v_max_f32_e32 v24, 0, v24
	v_pk_mul_f32 v[30:31], v[30:31], v[34:35] op_sel_hi:[1,0]
	v_max_f32_e32 v28, 0, v28
	v_mul_f32_e32 v35, v24, v24
	v_max_f32_e32 v24, 0, v29
	v_max_f32_e32 v25, 0, v25
	v_max_f32_e32 v26, 0, v26
	v_lshl_add_u64 v[32:33], v[140:141], 0, s[4:5]
	v_mul_f32_e32 v28, v28, v28
	v_mul_f32_e32 v24, v24, v24
	v_mul_f32_e32 v29, v25, v25
	v_max_f32_e32 v25, 0, v30
	v_mul_f32_e32 v30, v26, v26
	v_max_f32_e32 v26, 0, v31
	s_mov_b32 s4, 0x140000
	v_mul_f32_e32 v25, v25, v25
	v_max_f32_e32 v27, 0, v27
	v_mul_f32_e32 v26, v26, v26
	v_cvt_pk_bf16_f32 v24, v28, v24
	v_add_co_u32_e32 v28, vcc, s4, v140
	v_pk_mul_f32 v[18:19], v[18:19], v[34:35] op_sel_hi:[1,0]
	v_pk_mul_f32 v[16:17], v[16:17], v[34:35] op_sel_hi:[1,0]
	v_mul_f32_e32 v27, v27, v27
	v_cvt_pk_bf16_f32 v25, v25, v26
	v_cvt_pk_bf16_f32 v26, v35, v29
	v_addc_co_u32_e32 v29, vcc, 0, v141, vcc
	v_pk_mul_f32 v[22:23], v[22:23], v[34:35] op_sel_hi:[1,0]
	v_pk_mul_f32 v[20:21], v[20:21], v[34:35] op_sel_hi:[1,0]
	v_max_f32_e32 v16, 0, v16
	v_max_f32_e32 v17, 0, v17
	v_max_f32_e32 v18, 0, v18
	v_cvt_pk_bf16_f32 v27, v30, v27
	global_store_dwordx4 v[28:29], v[24:27], off
	v_max_f32_e32 v19, 0, v19
	v_max_f32_e32 v20, 0, v20
	v_mul_f32_e32 v24, v16, v16
	v_max_f32_e32 v16, 0, v21
	v_mul_f32_e32 v21, v17, v17
	v_max_f32_e32 v17, 0, v22
	v_mul_f32_e32 v22, v18, v18
	v_max_f32_e32 v18, 0, v23
	v_mul_f32_e32 v16, v16, v16
	v_mul_f32_e32 v17, v17, v17
	v_mul_f32_e32 v18, v18, v18
	v_mul_f32_e32 v19, v19, v19
	v_mul_f32_e32 v20, v20, v20
	v_cvt_pk_bf16_f32 v16, v20, v16
	v_cvt_pk_bf16_f32 v17, v17, v18
	v_cvt_pk_bf16_f32 v18, v24, v21
	v_cvt_pk_bf16_f32 v19, v22, v19
	global_store_dwordx4 v[32:33], v[16:19], off offset:256
	s_nop 1
	v_mov_b32_e32 v16, v170
	v_fmamk_f32 v16, v16, 0x3a800000, v235
	s_mov_b64 s[4:5], 0x160000
	v_rsq_f32_e32 v16, v16
	s_nop 0
	v_pk_mul_f32 v[8:9], v[8:9], v[16:17] op_sel_hi:[1,0]
	v_pk_mul_f32 v[12:13], v[12:13], v[16:17] op_sel_hi:[1,0]
	v_pk_mul_f32 v[10:11], v[10:11], v[16:17] op_sel_hi:[1,0]
	v_max_f32_e32 v8, 0, v8
	v_pk_mul_f32 v[14:15], v[14:15], v[16:17] op_sel_hi:[1,0]
	v_max_f32_e32 v12, 0, v12
	v_mul_f32_e32 v17, v8, v8
	v_max_f32_e32 v8, 0, v13
	v_max_f32_e32 v9, 0, v9
	v_max_f32_e32 v10, 0, v10
	v_lshl_add_u64 v[18:19], v[140:141], 0, s[4:5]
	v_mul_f32_e32 v12, v12, v12
	v_mul_f32_e32 v8, v8, v8
	v_mul_f32_e32 v13, v9, v9
	v_max_f32_e32 v9, 0, v14
	v_mul_f32_e32 v14, v10, v10
	v_max_f32_e32 v10, 0, v15
	s_mov_b32 s4, 0x160000
	v_mul_f32_e32 v9, v9, v9
	v_max_f32_e32 v11, 0, v11
	v_mul_f32_e32 v10, v10, v10
	v_cvt_pk_bf16_f32 v8, v12, v8
	v_add_co_u32_e32 v12, vcc, s4, v140
	v_pk_mul_f32 v[2:3], v[2:3], v[16:17] op_sel_hi:[1,0]
	v_pk_mul_f32 v[0:1], v[0:1], v[16:17] op_sel_hi:[1,0]
	v_mul_f32_e32 v11, v11, v11
	v_cvt_pk_bf16_f32 v9, v9, v10
	v_cvt_pk_bf16_f32 v10, v17, v13
	v_addc_co_u32_e32 v13, vcc, 0, v141, vcc
	v_pk_mul_f32 v[6:7], v[6:7], v[16:17] op_sel_hi:[1,0]
	v_pk_mul_f32 v[4:5], v[4:5], v[16:17] op_sel_hi:[1,0]
	v_max_f32_e32 v0, 0, v0
	v_max_f32_e32 v1, 0, v1
	v_max_f32_e32 v2, 0, v2
	v_cvt_pk_bf16_f32 v11, v14, v11
	global_store_dwordx4 v[12:13], v[8:11], off
	v_max_f32_e32 v3, 0, v3
	v_max_f32_e32 v4, 0, v4
	v_mul_f32_e32 v8, v0, v0
	v_max_f32_e32 v0, 0, v5
	v_mul_f32_e32 v5, v1, v1
	v_max_f32_e32 v1, 0, v6
	v_mul_f32_e32 v6, v2, v2
	v_max_f32_e32 v2, 0, v7
	v_mul_f32_e32 v0, v0, v0
	v_mul_f32_e32 v1, v1, v1
	v_mul_f32_e32 v2, v2, v2
	v_mul_f32_e32 v3, v3, v3
	s_andn2_b64 vcc, exec, s[38:39]
	v_mul_f32_e32 v4, v4, v4
	v_cvt_pk_bf16_f32 v0, v4, v0
	v_cvt_pk_bf16_f32 v1, v1, v2
	v_cvt_pk_bf16_f32 v2, v8, v5
	v_cvt_pk_bf16_f32 v3, v6, v3
	global_store_dwordx4 v[18:19], v[0:3], off offset:256
	s_cbranch_vccnz .LBB0_1136
	s_andn2_b64 vcc, exec, s[42:43]
	s_cbranch_vccnz .LBB0_1135
	s_barrier
	s_branch .LBB0_1135

.LBB0_1155:
	s_and_b32 s8, s6, 0xc0
	s_and_b32 s9, s4, 0xffffffc0
	v_or_b32_e32 v1, s8, v76
	v_or_b32_e32 v0, s9, v76
	v_lshlrev_b32_e32 v192, 11, v1
	v_ashrrev_i32_e32 v1, 31, v0
	v_lshlrev_b64 v[4:5], 11, v[0:1]
	v_lshl_add_u64 v[116:117], v[74:75], 0, v[4:5]
	v_add_co_u32_e32 v118, vcc, 0x10000, v116
	v_lshl_add_u64 v[114:115], v[72:73], 0, v[192:193]
	s_nop 0
	v_addc_co_u32_e32 v119, vcc, 0, v117, vcc
	v_add_co_u32_e32 v120, vcc, 0x10000, v114
	global_load_dwordx4 v[0:3], v[114:115], off
	s_nop 0
	v_addc_co_u32_e32 v121, vcc, 0, v115, vcc
	global_load_dwordx4 v[64:67], v[114:115], off offset:32
	global_load_dwordx4 v[4:7], v[116:117], off
	global_load_dwordx4 v[90:93], v[118:119], off offset:32
	global_load_dwordx4 v[20:23], v[120:121], off
	global_load_dwordx4 v[68:71], v[116:117], off offset:32
	global_load_dwordx4 v[16:19], v[118:119], off
	global_load_dwordx4 v[94:97], v[120:121], off offset:32
	v_add_u32_e32 v89, 0x800, v77
	s_add_i32 s2, s2, s56
	s_add_i32 s4, s4, s5
	s_add_i32 s6, s6, s7
	s_cmpk_lt_i32 s2, 0x100
	s_waitcnt vmcnt(5)
	v_mfma_f32_32x32x16_bf16 v[32:47], v[0:3], v[4:7], 0
	s_waitcnt vmcnt(1)
	v_mfma_f32_32x32x16_bf16 v[48:63], v[0:3], v[16:19], 0
	v_mfma_f32_32x32x16_bf16 v[0:15], v[20:23], v[4:7], 0
	v_mfma_f32_32x32x16_bf16 v[16:31], v[20:23], v[16:19], 0
	v_mfma_f32_32x32x16_bf16 v[32:47], v[64:67], v[68:71], v[32:47]
	v_mfma_f32_32x32x16_bf16 v[48:63], v[64:67], v[90:93], v[48:63]
	global_load_dwordx4 v[64:67], v[114:115], off offset:64
	global_load_dwordx4 v[98:101], v[114:115], off offset:96
	s_waitcnt vmcnt(2)
	v_mfma_f32_32x32x16_bf16 v[0:15], v[94:97], v[68:71], v[0:15]
	global_load_dwordx4 v[68:71], v[116:117], off offset:64
	global_load_dwordx4 v[102:105], v[116:117], off offset:96
	v_mfma_f32_32x32x16_bf16 v[16:31], v[94:97], v[90:93], v[16:31]
	global_load_dwordx4 v[90:93], v[118:119], off offset:64
	global_load_dwordx4 v[94:97], v[118:119], off offset:96
	global_load_dwordx4 v[106:109], v[120:121], off offset:64
	s_waitcnt vmcnt(4)
	v_mfma_f32_32x32x16_bf16 v[32:47], v[64:67], v[68:71], v[32:47]
	s_waitcnt vmcnt(2)
	v_mfma_f32_32x32x16_bf16 v[48:63], v[64:67], v[90:93], v[48:63]
	global_load_dwordx4 v[64:67], v[120:121], off offset:96
	s_waitcnt vmcnt(1)
	v_mfma_f32_32x32x16_bf16 v[0:15], v[106:109], v[68:71], v[0:15]
	v_mfma_f32_32x32x16_bf16 v[16:31], v[106:109], v[90:93], v[16:31]
	global_load_dwordx4 v[68:71], v[114:115], off offset:128
	global_load_dwordx4 v[90:93], v[114:115], off offset:160
	v_mfma_f32_32x32x16_bf16 v[32:47], v[98:101], v[102:105], v[32:47]
	v_mfma_f32_32x32x16_bf16 v[48:63], v[98:101], v[94:97], v[48:63]
	s_waitcnt vmcnt(2)
	v_mfma_f32_32x32x16_bf16 v[0:15], v[64:67], v[102:105], v[0:15]
	global_load_dwordx4 v[98:101], v[116:117], off offset:128
	global_load_dwordx4 v[102:105], v[116:117], off offset:160
	v_mfma_f32_32x32x16_bf16 v[16:31], v[64:67], v[94:97], v[16:31]
	global_load_dwordx4 v[64:67], v[118:119], off offset:128
	global_load_dwordx4 v[94:97], v[118:119], off offset:160
	global_load_dwordx4 v[106:109], v[120:121], off offset:128
	global_load_dwordx4 v[110:113], v[120:121], off offset:160
	s_waitcnt vmcnt(5)
	v_mfma_f32_32x32x16_bf16 v[32:47], v[68:71], v[98:101], v[32:47]
	s_waitcnt vmcnt(3)
	v_mfma_f32_32x32x16_bf16 v[48:63], v[68:71], v[64:67], v[48:63]
	s_waitcnt vmcnt(1)
	v_mfma_f32_32x32x16_bf16 v[0:15], v[106:109], v[98:101], v[0:15]
	v_mfma_f32_32x32x16_bf16 v[16:31], v[106:109], v[64:67], v[16:31]
	v_mfma_f32_32x32x16_bf16 v[32:47], v[90:93], v[102:105], v[32:47]
	v_mfma_f32_32x32x16_bf16 v[48:63], v[90:93], v[94:97], v[48:63]
	global_load_dwordx4 v[90:93], v[114:115], off offset:192
	global_load_dwordx4 v[98:101], v[114:115], off offset:224
	s_waitcnt vmcnt(2)
	v_mfma_f32_32x32x16_bf16 v[0:15], v[110:113], v[102:105], v[0:15]
	global_load_dwordx4 v[102:105], v[116:117], off offset:192
	global_load_dwordx4 v[68:71], v[116:117], off offset:224
	v_mfma_f32_32x32x16_bf16 v[16:31], v[110:113], v[94:97], v[16:31]
	global_load_dwordx4 v[94:97], v[118:119], off offset:192
	global_load_dwordx4 v[64:67], v[118:119], off offset:224
	global_load_dwordx4 v[106:109], v[120:121], off offset:192
	s_waitcnt vmcnt(4)
	v_mfma_f32_32x32x16_bf16 v[32:47], v[90:93], v[102:105], v[32:47]
	s_waitcnt vmcnt(2)
	v_mfma_f32_32x32x16_bf16 v[48:63], v[90:93], v[94:97], v[48:63]
	global_load_dwordx4 v[90:93], v[120:121], off offset:224
	s_waitcnt vmcnt(1)
	v_mfma_f32_32x32x16_bf16 v[0:15], v[106:109], v[102:105], v[0:15]
	v_add_u32_e32 v102, 0x1000, v77
	v_add_u32_e32 v103, 0x1800, v77
	v_add_u32_e32 v104, 0x2000, v77
	v_add_u32_e32 v105, 0x2800, v77
	v_mfma_f32_32x32x16_bf16 v[16:31], v[106:109], v[94:97], v[16:31]
	v_add_u32_e32 v96, s8, v78
	v_ashrrev_i32_e32 v97, 31, v96
	v_or_b32_e32 v94, s9, v79
	v_ashrrev_i32_e32 v95, 31, v94
	v_mfma_f32_32x32x16_bf16 v[32:47], v[98:101], v[68:71], v[32:47]
	v_mfma_f32_32x32x16_bf16 v[48:63], v[98:101], v[64:67], v[48:63]
	v_add_u32_e32 v98, 0x3000, v77
	v_add_u32_e32 v99, 0x3800, v77
	s_waitcnt vmcnt(0)
	v_mfma_f32_32x32x16_bf16 v[0:15], v[90:93], v[68:71], v[0:15]
	v_lshl_add_u64 v[68:69], v[96:97], 2, s[30:31]
	v_lshlrev_b64 v[70:71], 13, v[96:97]
	v_lshl_add_u64 v[70:71], s[22:23], 0, v[70:71]
	v_lshl_add_u64 v[70:71], v[94:95], 1, v[70:71]
	v_mfma_f32_32x32x16_bf16 v[16:31], v[90:93], v[64:67], v[16:31]
	s_nop 2
	ds_write2_b32 v77, v32, v48 offset1:32
	ds_write2_b32 v77, v33, v49 offset0:64 offset1:96
	ds_write2_b32 v77, v34, v50 offset0:128 offset1:160
	ds_write2_b32 v77, v35, v51 offset0:192 offset1:224
	ds_write2_b32 v89, v36, v52 offset1:32
	ds_write2_b32 v89, v37, v53 offset0:64 offset1:96
	ds_write2_b32 v89, v38, v54 offset0:128 offset1:160
	ds_write2_b32 v89, v39, v55 offset0:192 offset1:224
	ds_write2_b32 v102, v40, v56 offset1:32
	ds_write2_b32 v102, v41, v57 offset0:64 offset1:96
	ds_write2_b32 v102, v42, v58 offset0:128 offset1:160
	ds_write2_b32 v102, v43, v59 offset0:192 offset1:224
	ds_write2_b32 v103, v44, v60 offset1:32
	ds_write2_b32 v103, v45, v61 offset0:64 offset1:96
	ds_write2_b32 v103, v46, v62 offset0:128 offset1:160
	ds_write2_b32 v103, v47, v63 offset0:192 offset1:224
	ds_write2_b32 v104, v0, v16 offset1:32
	ds_write2_b32 v104, v1, v17 offset0:64 offset1:96
	ds_write2_b32 v104, v2, v18 offset0:128 offset1:160
	ds_write2_b32 v104, v3, v19 offset0:192 offset1:224
	ds_write2_b32 v105, v4, v20 offset1:32
	ds_write2_b32 v105, v5, v21 offset0:64 offset1:96
	ds_write2_b32 v105, v6, v22 offset0:128 offset1:160
	ds_write2_b32 v105, v7, v23 offset0:192 offset1:224
	ds_write2_b32 v98, v8, v24 offset1:32
	ds_write2_b32 v98, v9, v25 offset0:64 offset1:96
	ds_write2_b32 v98, v10, v26 offset0:128 offset1:160
	ds_write2_b32 v98, v11, v27 offset0:192 offset1:224
	ds_write2_b32 v99, v12, v28 offset1:32
	ds_write2_b32 v99, v13, v29 offset0:64 offset1:96
	ds_write2_b32 v99, v14, v30 offset0:128 offset1:160
	ds_write2_b32 v99, v15, v31 offset0:192 offset1:224
	s_waitcnt lgkmcnt(0)
	s_barrier
	global_load_dword v64, v[68:69], off
	ds_read_b128 v[0:3], v81
	ds_read_b128 v[4:7], v82
	ds_read_b128 v[8:11], v83
	ds_read_b128 v[12:15], v84
	ds_read_b128 v[16:19], v80
	ds_read_b128 v[20:23], v80 offset:16
	ds_read_b128 v[24:27], v85
	ds_read_b128 v[28:31], v86
	ds_read_b128 v[32:35], v87
	ds_read_b128 v[36:39], v88
	ds_read_b128 v[40:43], v80 offset:55312
	ds_read_b128 v[44:47], v80 offset:55296
	ds_read_b128 v[48:51], v80 offset:36880
	ds_read_b128 v[52:55], v80 offset:36864
	ds_read_b128 v[56:59], v80 offset:18448
	ds_read_b128 v[60:63], v80 offset:18432
	s_waitcnt lgkmcnt(10)
	v_add_f32_e32 v20, 0, v20
	v_add_f32_e32 v21, 0, v21
	v_add_f32_e32 v22, 0, v22
	s_waitcnt lgkmcnt(1)
	v_add_f32_e32 v20, v56, v20
	v_add_f32_e32 v21, v57, v21
	v_add_f32_e32 v20, v48, v20
	v_add_f32_e32 v21, v49, v21
	v_add_f32_e32 v20, v40, v20
	v_add_f32_e32 v21, v41, v21
	v_add_f32_e32 v12, v12, v20
	v_add_f32_e32 v13, v13, v21
	v_add_f32_e32 v8, v8, v12
	v_add_f32_e32 v9, v9, v13
	v_add_f32_e32 v4, v4, v8
	v_add_f32_e32 v5, v5, v9
	v_add_f32_e32 v0, v0, v4
	v_add_f32_e32 v23, 0, v23
	v_add_f32_e32 v16, 0, v16
	v_add_f32_e32 v17, 0, v17
	v_add_f32_e32 v22, v58, v22
	v_add_f32_e32 v1, v1, v5
	v_add_f32_e32 v18, 0, v18
	v_add_f32_e32 v23, v59, v23
	s_waitcnt lgkmcnt(0)
	v_add_f32_e32 v16, v60, v16
	v_add_f32_e32 v17, v61, v17
	v_add_f32_e32 v22, v50, v22
	v_add_f32_e32 v18, v62, v18
	v_add_f32_e32 v23, v51, v23
	v_add_f32_e32 v16, v52, v16
	v_add_f32_e32 v17, v53, v17
	v_add_f32_e32 v22, v42, v22
	v_add_f32_e32 v18, v54, v18
	v_add_f32_e32 v23, v43, v23
	v_add_f32_e32 v16, v44, v16
	v_add_f32_e32 v17, v45, v17
	v_add_f32_e32 v14, v14, v22
	v_add_f32_e32 v18, v46, v18
	v_add_f32_e32 v15, v15, v23
	v_add_f32_e32 v16, v36, v16
	v_add_f32_e32 v17, v37, v17
	v_add_f32_e32 v10, v10, v14
	v_add_f32_e32 v18, v38, v18
	v_add_f32_e32 v11, v11, v15
	v_add_f32_e32 v15, v32, v16
	v_add_f32_e32 v16, v33, v17
	v_add_f32_e32 v6, v6, v10
	v_add_f32_e32 v17, v34, v18
	v_add_f32_e32 v7, v7, v11
	v_add_f32_e32 v11, v28, v15
	v_add_f32_e32 v12, v29, v16
	v_add_f32_e32 v2, v2, v6
	v_add_f32_e32 v13, v30, v17
	v_add_f32_e32 v3, v3, v7
	v_add_f32_e32 v7, v24, v11
	v_add_f32_e32 v8, v25, v12
	v_add_f32_e32 v9, v26, v13
	v_add_f32_e32 v19, 0, v19
	v_add_f32_e32 v19, v63, v19
	v_add_f32_e32 v19, v55, v19
	v_add_f32_e32 v19, v47, v19
	v_add_f32_e32 v19, v39, v19
	v_add_f32_e32 v18, v35, v19
	v_add_f32_e32 v14, v31, v18
	v_add_f32_e32 v10, v27, v14
	s_waitcnt vmcnt(0)
	v_fmamk_f32 v4, v64, 0x3a800000, v235
	v_rsq_f32_e32 v4, v4
	s_nop 0
	v_mul_f32_e32 v3, v4, v3
	v_mul_f32_e32 v5, v4, v7
	v_mul_f32_e32 v6, v4, v8
	v_mul_f32_e32 v7, v4, v9
	v_mul_f32_e32 v8, v4, v10
	v_mul_f32_e32 v0, v4, v0
	v_mul_f32_e32 v9, v4, v1
	v_mul_f32_e32 v10, v4, v2
	v_max_f32_e32 v1, 0, v3
	v_max_f32_e32 v2, 0, v5
	v_max_f32_e32 v3, 0, v6
	v_max_f32_e32 v4, 0, v7
	v_max_f32_e32 v5, 0, v8
	v_max_f32_e32 v6, 0, v0
	v_max_f32_e32 v7, 0, v9
	v_max_f32_e32 v0, 0, v10
	v_pk_mul_f32 v[2:3], v[2:3], v[2:3]
	v_pk_mul_f32 v[4:5], v[4:5], v[4:5]
	v_pk_mul_f32 v[6:7], v[6:7], v[6:7]
	v_pk_mul_f32 v[8:9], v[0:1], v[0:1]
	v_cvt_pk_bf16_f32 v0, v2, v3
	v_cvt_pk_bf16_f32 v1, v4, v5
	v_cvt_pk_bf16_f32 v2, v6, v7
	v_cvt_pk_bf16_f32 v3, v8, v9
	global_store_dwordx4 v[70:71], v[0:3], off
	s_barrier
	s_cbranch_scc1 .LBB0_1155
